# hyena in-proj GEMM epilogue: row scales computed once by leading half and shared via LDS (same as FFN-in), epilogue regenerated with identical math
# speedup vs baseline: 1.0020x; 1.0020x over previous
; #define PG8_STAGE(bufoff, gbase, voff) do { _Pragma("unroll") for (int _i = 0; _i < 2; ++_i) \
;         __builtin_amdgcn_global_load_lds((const unsigned*)((const char*)(gbase) + (voff)[_i]), (PG8_LAS unsigned*)(lds + (bufoff) + ldsw + _i * 8192), 16, 0, 0); } while (0)
; #define PG8_LDA(dst, b, h) do { _Pragma("unroll") for (int m = 0; m < 4; ++m) _Pragma("unroll") for (int k = 0; k < 2; ++k) dst[m][k] = *(const PG8_LAS bf16x8*)(lds + PG8_SA(b, h) + aoff + m * 2048 + k * 1024); } while (0)
; #define PG8_LDB(dst, b, h) do { _Pragma("unroll") for (int n = 0; n < 2; ++n) _Pragma("unroll") for (int k = 0; k < 2; ++k) dst[n][k] = *(const PG8_LAS bf16x8*)(lds + PG8_SB(b, h) + boff + n * 2048 + k * 1024); } while (0)
; #define PG8_MMA(ai, bj, At, Bt) do { __builtin_amdgcn_s_setprio(1); _Pragma("unroll") for (int m = 0; m < 4; ++m) _Pragma("unroll") for (int n = 0; n < 2; ++n) _Pragma("unroll") for (int k = 0; k < 2; ++k) \
;         acc[ai][bj][m][n] = __builtin_amdgcn_mfma_f32_16x16x32_bf16(Bt[n][k], At[m][k], acc[ai][bj][m][n], 0, 0, 0); __builtin_amdgcn_s_setprio(0); } while (0)
; #define PG8_WAIT_V(n) asm volatile("s_waitcnt vmcnt(" #n ")" ::: "memory")
; template <class Epi, class Sched, bool ALIGN_EPI = false, bool SP2 = false>
; __device__ __forceinline__ void gemm_phase(PG8_LAS unsigned char* lds, const Gemm g, const Sched& S, const Epi& E) {
;     ...
;             PG8_LDB(B0, 0, 0); PG8_LDB(B1, 0, 1); PG8_SCHED; PG8_LDA(At, 0, 0); PG8_STAGE(PG8_SA(1, 1), a1 + hstep, voffA);
;             PG8_WAIT_V(8); PG8_WAIT_L(0); PG8_BAR; PG8_MMA(0, 0, At, B0); PG8_MMA(0, 1, At, B1); PG8_BAR; PG8_SCHED;
;             PG8_LDA(At, 0, 1); PG8_STAGE(PG8_SB(0, 0), b2, voffB); PG8_STAGE(PG8_SB(0, 1), b2 + hstep, voffB); PG8_STAGE(PG8_SA(0, 0), a2, voffA);
;             PG8_WAIT_V(8); PG8_WAIT_L(0); PG8_BAR; PG8_MMA(1, 0, At, B0); PG8_MMA(1, 1, At, B1); PG8_BAR; PG8_SCHED;
;             PG8_LDB(B0, 1, 0); PG8_LDB(B1, 1, 1); PG8_SCHED; PG8_LDA(At, 1, 0); PG8_STAGE(PG8_SA(0, 1), a2 + hstep, voffA);
;             PG8_WAIT_V(8); PG8_WAIT_L(0); PG8_BAR; PG8_MMA(0, 0, At, B0); PG8_MMA(0, 1, At, B1); PG8_BAR; PG8_SCHED;
;             PG8_LDA(At, 1, 1); PG8_STAGE(PG8_SB(1, 0), b3, voffB); PG8_STAGE(PG8_SB(1, 1), b3 + hstep, voffB); PG8_STAGE(PG8_SA(1, 0), a3, voffA);
;             PG8_WAIT_V(8); PG8_WAIT_L(0); PG8_BAR; PG8_MMA(1, 0, At, B0); PG8_MMA(1, 1, At, B1); PG8_BAR; PG8_SCHED;
.LBB0_360:
	s_add_u32 s54, s8, 0xfffc0080
	s_addc_u32 s55, s9, -1
	s_add_i32 s76, 0, 0x10000
	s_cmp_eq_u32 s73, 12
	s_cselect_b32 s61, s22, s55
	s_cselect_b32 s60, s23, s54
	s_cselect_b32 s55, s43, s63
	s_cselect_b32 s54, s45, s62
	s_add_i32 s92, 0, 0x14000
	v_add_u32_e32 v140, s76, v217
	v_add_u32_e32 v156, s92, v217
	ds_read_b128 v[128:131], v140
	ds_read_b128 v[132:135], v140 offset:1024
	ds_read_b128 v[136:139], v140 offset:2048
	ds_read_b128 v[140:143], v140 offset:3072
	ds_read_b128 v[144:147], v156
	ds_read_b128 v[148:151], v156 offset:1024
	ds_read_b128 v[152:155], v156 offset:2048
	ds_read_b128 v[156:159], v156 offset:3072
	v_lshl_add_u64 v[202:203], s[8:9], 0, v[176:177]
	s_add_i32 m0, s47, 0xc000
	ds_read_b128 v[160:163], v219
	ds_read_b128 v[164:167], v219 offset:1024
	ds_read_b128 v[186:189], v219 offset:2048
	ds_read_b128 v[190:193], v219 offset:3072
	ds_read_b128 v[194:197], v219 offset:4096
	ds_read_b128 v[198:201], v219 offset:5120
	ds_read_b128 v[224:227], v219 offset:6144
	ds_read_b128 v[230:233], v219 offset:7168
	global_load_lds_dwordx4 v[202:203], off
	v_lshl_add_u64 v[202:203], s[8:9], 0, v[178:179]
	s_add_i32 m0, s47, 0xe000
	s_nop 0
	global_load_lds_dwordx4 v[202:203], off
	s_waitcnt vmcnt(8)
	s_waitcnt lgkmcnt(0)
	s_setprio 1
	s_barrier
	v_mfma_f32_16x16x32_bf16 v[124:127], v[128:131], v[160:163], v[124:127]
	v_mfma_f32_16x16x32_bf16 v[120:123], v[136:139], v[160:163], v[120:123]
	v_mfma_f32_16x16x32_bf16 v[112:115], v[128:131], v[186:189], v[112:115]
	v_mfma_f32_16x16x32_bf16 v[104:107], v[136:139], v[186:189], v[104:107]
	v_mfma_f32_16x16x32_bf16 v[96:99], v[128:131], v[194:197], v[96:99]
	v_mfma_f32_16x16x32_bf16 v[88:91], v[136:139], v[194:197], v[88:91]
	v_mfma_f32_16x16x32_bf16 v[80:83], v[128:131], v[224:227], v[80:83]
	v_mfma_f32_16x16x32_bf16 v[72:75], v[136:139], v[224:227], v[72:75]
	v_mfma_f32_16x16x32_bf16 v[124:127], v[132:135], v[164:167], v[124:127]
	v_mfma_f32_16x16x32_bf16 v[120:123], v[140:143], v[164:167], v[120:123]
	v_mfma_f32_16x16x32_bf16 v[112:115], v[132:135], v[190:193], v[112:115]
	v_mfma_f32_16x16x32_bf16 v[104:107], v[140:143], v[190:193], v[104:107]
	v_mfma_f32_16x16x32_bf16 v[96:99], v[132:135], v[198:201], v[96:99]
	v_mfma_f32_16x16x32_bf16 v[88:91], v[140:143], v[198:201], v[88:91]
	v_mfma_f32_16x16x32_bf16 v[80:83], v[132:135], v[230:233], v[80:83]
	v_mfma_f32_16x16x32_bf16 v[72:75], v[140:143], v[230:233], v[72:75]
	s_setprio 0
	s_setprio 1
	v_mfma_f32_16x16x32_bf16 v[116:119], v[144:147], v[160:163], v[116:119]
	v_mfma_f32_16x16x32_bf16 v[108:111], v[152:155], v[160:163], v[108:111]
	v_mfma_f32_16x16x32_bf16 v[100:103], v[144:147], v[186:189], v[100:103]
	v_mfma_f32_16x16x32_bf16 v[92:95], v[152:155], v[186:189], v[92:95]
	v_mfma_f32_16x16x32_bf16 v[84:87], v[144:147], v[194:197], v[84:87]
	v_mfma_f32_16x16x32_bf16 v[76:79], v[152:155], v[194:197], v[76:79]
	v_mfma_f32_16x16x32_bf16 v[68:71], v[144:147], v[224:227], v[68:71]
	v_mfma_f32_16x16x32_bf16 v[64:67], v[152:155], v[224:227], v[64:67]
	v_mfma_f32_16x16x32_bf16 v[116:119], v[148:151], v[164:167], v[116:119]
	v_mfma_f32_16x16x32_bf16 v[108:111], v[156:159], v[164:167], v[108:111]
	v_mfma_f32_16x16x32_bf16 v[100:103], v[148:151], v[190:193], v[100:103]
	v_mfma_f32_16x16x32_bf16 v[92:95], v[156:159], v[190:193], v[92:95]
	v_mfma_f32_16x16x32_bf16 v[84:87], v[148:151], v[198:201], v[84:87]
	v_mfma_f32_16x16x32_bf16 v[76:79], v[156:159], v[198:201], v[76:79]
	v_mfma_f32_16x16x32_bf16 v[68:71], v[148:151], v[230:233], v[68:71]
	v_mfma_f32_16x16x32_bf16 v[64:67], v[156:159], v[230:233], v[64:67]
	s_barrier
	s_setprio 0
	s_add_i32 s76, s76, s46
	v_lshl_add_u64 v[202:203], s[54:55], 0, v[180:181]
	s_mov_b32 m0, s76
	ds_read_b128 v[160:163], v219 offset:16384
	ds_read_b128 v[164:167], v219 offset:17408
	ds_read_b128 v[186:189], v219 offset:18432
	ds_read_b128 v[190:193], v219 offset:19456
	ds_read_b128 v[194:197], v219 offset:20480
	ds_read_b128 v[198:201], v219 offset:21504
	ds_read_b128 v[224:227], v219 offset:22528
	ds_read_b128 v[230:233], v219 offset:23552
	global_load_lds_dwordx4 v[202:203], off
	s_add_i32 m0, s76, 0x2000
	s_add_u32 s76, s54, 0x40000
	v_lshl_add_u64 v[208:209], s[54:55], 0, v[168:169]
	s_addc_u32 s77, s55, 0
	s_add_i32 s92, s92, s46
	global_load_lds_dwordx4 v[208:209], off
	v_lshl_add_u64 v[220:221], s[76:77], 0, v[180:181]
	s_mov_b32 m0, s92
	v_lshl_add_u64 v[234:235], s[60:61], 0, v[170:171]
	global_load_lds_dwordx4 v[220:221], off
	v_lshl_add_u64 v[220:221], s[76:77], 0, v[168:169]
	s_add_i32 m0, s92, 0x2000
	s_nop 0
	global_load_lds_dwordx4 v[220:221], off
	v_lshl_add_u64 v[220:221], s[60:61], 0, v[172:173]
	s_mov_b32 m0, s47
	s_nop 0
	global_load_lds_dwordx4 v[220:221], off
	s_mov_b32 m0, s56
	s_nop 0
	global_load_lds_dwordx4 v[234:235], off
	s_waitcnt vmcnt(8)
	s_waitcnt lgkmcnt(0)
	s_setprio 1
	s_barrier
; #define PG8_STAGE(bufoff, gbase, voff) do { _Pragma("unroll") for (int _i = 0; _i < 2; ++_i) \
;         __builtin_amdgcn_global_load_lds((const unsigned*)((const char*)(gbase) + (voff)[_i]), (PG8_LAS unsigned*)(lds + (bufoff) + ldsw + _i * 8192), 16, 0, 0); } while (0)
; #define PG8_LDA(dst, b, h) do { _Pragma("unroll") for (int m = 0; m < 4; ++m) _Pragma("unroll") for (int k = 0; k < 2; ++k) dst[m][k] = *(const PG8_LAS bf16x8*)(lds + PG8_SA(b, h) + aoff + m * 2048 + k * 1024); } while (0)
; #define PG8_LDB(dst, b, h) do { _Pragma("unroll") for (int n = 0; n < 2; ++n) _Pragma("unroll") for (int k = 0; k < 2; ++k) dst[n][k] = *(const PG8_LAS bf16x8*)(lds + PG8_SB(b, h) + boff + n * 2048 + k * 1024); } while (0)
; #define PG8_MMA(ai, bj, At, Bt) do { __builtin_amdgcn_s_setprio(1); _Pragma("unroll") for (int m = 0; m < 4; ++m) _Pragma("unroll") for (int n = 0; n < 2; ++n) _Pragma("unroll") for (int k = 0; k < 2; ++k) \
;         acc[ai][bj][m][n] = __builtin_amdgcn_mfma_f32_16x16x32_bf16(Bt[n][k], At[m][k], acc[ai][bj][m][n], 0, 0, 0); __builtin_amdgcn_s_setprio(0); } while (0)
; #define PG8_WAIT_V(n) asm volatile("s_waitcnt vmcnt(" #n ")" ::: "memory")
; #define PG8_WAIT_L(n) asm volatile("s_waitcnt lgkmcnt(" #n ")" ::: "memory")
; #define PG8_BAR __builtin_amdgcn_s_barrier()
; #define PG8_SCHED __builtin_amdgcn_sched_barrier(0)
; template <class Epi, class Sched, bool ALIGN_EPI = false, bool SP2 = false>
; __device__ __forceinline__ void gemm_phase(PG8_LAS unsigned char* lds, const Gemm g, const Sched& S, const Epi& E) {
;     ...
;             PG8_LDB(B0, 0, 0); PG8_LDB(B1, 0, 1); PG8_SCHED; PG8_LDA(At, 0, 0); PG8_STAGE(PG8_SA(1, 1), a1 + hstep, voffA);
;             PG8_WAIT_V(8); PG8_WAIT_L(0); PG8_BAR; PG8_MMA(0, 0, At, B0); PG8_MMA(0, 1, At, B1); PG8_BAR; PG8_SCHED;
;             PG8_LDA(At, 0, 1); PG8_STAGE(PG8_SB(0, 0), b2, voffB); PG8_STAGE(PG8_SB(0, 1), b2 + hstep, voffB); PG8_STAGE(PG8_SA(0, 0), a2, voffA);
;             PG8_WAIT_V(8); PG8_WAIT_L(0); PG8_BAR; PG8_MMA(1, 0, At, B0); PG8_MMA(1, 1, At, B1); PG8_BAR; PG8_SCHED;
;             PG8_LDB(B0, 1, 0); PG8_LDB(B1, 1, 1); PG8_SCHED; PG8_LDA(At, 1, 0); PG8_STAGE(PG8_SA(0, 1), a2 + hstep, voffA);
;             PG8_WAIT_V(8); PG8_WAIT_L(0); PG8_BAR; PG8_MMA(0, 0, At, B0); PG8_MMA(0, 1, At, B1); PG8_BAR; PG8_SCHED;
	v_mfma_f32_16x16x32_bf16 v[60:63], v[128:131], v[160:163], v[60:63]
	v_mfma_f32_16x16x32_bf16 v[56:59], v[136:139], v[160:163], v[56:59]
	v_mfma_f32_16x16x32_bf16 v[48:51], v[128:131], v[186:189], v[48:51]
	v_mfma_f32_16x16x32_bf16 v[40:43], v[136:139], v[186:189], v[40:43]
	v_mfma_f32_16x16x32_bf16 v[32:35], v[128:131], v[194:197], v[32:35]
	v_mfma_f32_16x16x32_bf16 v[24:27], v[136:139], v[194:197], v[24:27]
	v_mfma_f32_16x16x32_bf16 v[16:19], v[128:131], v[224:227], v[16:19]
	v_mfma_f32_16x16x32_bf16 v[8:11], v[136:139], v[224:227], v[8:11]
	v_mfma_f32_16x16x32_bf16 v[60:63], v[132:135], v[164:167], v[60:63]
	v_mfma_f32_16x16x32_bf16 v[56:59], v[140:143], v[164:167], v[56:59]
	v_mfma_f32_16x16x32_bf16 v[48:51], v[132:135], v[190:193], v[48:51]
	v_mfma_f32_16x16x32_bf16 v[40:43], v[140:143], v[190:193], v[40:43]
	v_mfma_f32_16x16x32_bf16 v[32:35], v[132:135], v[198:201], v[32:35]
	v_mfma_f32_16x16x32_bf16 v[24:27], v[140:143], v[198:201], v[24:27]
	v_mfma_f32_16x16x32_bf16 v[16:19], v[132:135], v[230:233], v[16:19]
	v_mfma_f32_16x16x32_bf16 v[8:11], v[140:143], v[230:233], v[8:11]
	s_setprio 0
	s_setprio 1
	v_mfma_f32_16x16x32_bf16 v[52:55], v[144:147], v[160:163], v[52:55]
	v_mfma_f32_16x16x32_bf16 v[44:47], v[152:155], v[160:163], v[44:47]
	v_mfma_f32_16x16x32_bf16 v[36:39], v[144:147], v[186:189], v[36:39]
	v_mfma_f32_16x16x32_bf16 v[28:31], v[152:155], v[186:189], v[28:31]
	v_mfma_f32_16x16x32_bf16 v[20:23], v[144:147], v[194:197], v[20:23]
	v_mfma_f32_16x16x32_bf16 v[12:15], v[152:155], v[194:197], v[12:15]
	v_mfma_f32_16x16x32_bf16 v[4:7], v[144:147], v[224:227], v[4:7]
	v_mfma_f32_16x16x32_bf16 v[0:3], v[152:155], v[224:227], v[0:3]
	v_mfma_f32_16x16x32_bf16 v[52:55], v[148:151], v[164:167], v[52:55]
	v_mfma_f32_16x16x32_bf16 v[44:47], v[156:159], v[164:167], v[44:47]
	v_mfma_f32_16x16x32_bf16 v[36:39], v[148:151], v[190:193], v[36:39]
	v_mfma_f32_16x16x32_bf16 v[28:31], v[156:159], v[190:193], v[28:31]
	v_mfma_f32_16x16x32_bf16 v[20:23], v[148:151], v[198:201], v[20:23]
	v_mfma_f32_16x16x32_bf16 v[12:15], v[156:159], v[198:201], v[12:15]
	v_mfma_f32_16x16x32_bf16 v[4:7], v[148:151], v[230:233], v[4:7]
	v_mfma_f32_16x16x32_bf16 v[0:3], v[156:159], v[230:233], v[0:3]
	s_barrier
	s_setprio 0
	s_add_i32 s76, 0, 0x18000
	s_add_i32 s77, 0, 0x1c000
	v_add_u32_e32 v140, s76, v217
	v_add_u32_e32 v156, s77, v217
	ds_read_b128 v[128:131], v140
	ds_read_b128 v[132:135], v140 offset:1024
	ds_read_b128 v[136:139], v140 offset:2048
	ds_read_b128 v[140:143], v140 offset:3072
	ds_read_b128 v[144:147], v156
	ds_read_b128 v[148:151], v156 offset:1024
	ds_read_b128 v[152:155], v156 offset:2048
	ds_read_b128 v[156:159], v156 offset:3072
	s_add_u32 s60, s60, 0x40000
	s_addc_u32 s61, s61, 0
	s_mov_b32 m0, s57
	v_lshl_add_u64 v[236:237], s[60:61], 0, v[172:173]
	ds_read_b128 v[160:163], v219 offset:32768
	ds_read_b128 v[164:167], v219 offset:33792
	ds_read_b128 v[186:189], v219 offset:34816
	ds_read_b128 v[190:193], v219 offset:35840
	ds_read_b128 v[194:197], v219 offset:36864
	ds_read_b128 v[198:201], v219 offset:37888
	ds_read_b128 v[224:227], v219 offset:38912
	ds_read_b128 v[230:233], v219 offset:39936
	global_load_lds_dwordx4 v[236:237], off
	v_lshl_add_u64 v[236:237], s[60:61], 0, v[170:171]
	s_mov_b32 m0, s58
	s_nop 0
	global_load_lds_dwordx4 v[236:237], off
	s_waitcnt vmcnt(8)
	s_waitcnt lgkmcnt(0)
	s_setprio 1
	s_barrier
	v_mfma_f32_16x16x32_bf16 v[124:127], v[128:131], v[160:163], v[124:127]
	v_mfma_f32_16x16x32_bf16 v[120:123], v[136:139], v[160:163], v[120:123]
	v_mfma_f32_16x16x32_bf16 v[112:115], v[128:131], v[186:189], v[112:115]
	v_mfma_f32_16x16x32_bf16 v[104:107], v[136:139], v[186:189], v[104:107]
	v_mfma_f32_16x16x32_bf16 v[96:99], v[128:131], v[194:197], v[96:99]
	v_mfma_f32_16x16x32_bf16 v[88:91], v[136:139], v[194:197], v[88:91]
	v_mfma_f32_16x16x32_bf16 v[80:83], v[128:131], v[224:227], v[80:83]
	v_mfma_f32_16x16x32_bf16 v[72:75], v[136:139], v[224:227], v[72:75]
	v_mfma_f32_16x16x32_bf16 v[124:127], v[132:135], v[164:167], v[124:127]
	v_mfma_f32_16x16x32_bf16 v[120:123], v[140:143], v[164:167], v[120:123]
	v_mfma_f32_16x16x32_bf16 v[112:115], v[132:135], v[190:193], v[112:115]
	v_mfma_f32_16x16x32_bf16 v[104:107], v[140:143], v[190:193], v[104:107]
	v_mfma_f32_16x16x32_bf16 v[96:99], v[132:135], v[198:201], v[96:99]
	v_mfma_f32_16x16x32_bf16 v[88:91], v[140:143], v[198:201], v[88:91]
	v_mfma_f32_16x16x32_bf16 v[80:83], v[132:135], v[230:233], v[80:83]
	v_mfma_f32_16x16x32_bf16 v[72:75], v[140:143], v[230:233], v[72:75]
	s_setprio 0
	s_setprio 1
	v_mfma_f32_16x16x32_bf16 v[116:119], v[144:147], v[160:163], v[116:119]
	v_mfma_f32_16x16x32_bf16 v[108:111], v[152:155], v[160:163], v[108:111]
	v_mfma_f32_16x16x32_bf16 v[100:103], v[144:147], v[186:189], v[100:103]
	v_mfma_f32_16x16x32_bf16 v[92:95], v[152:155], v[186:189], v[92:95]
	v_mfma_f32_16x16x32_bf16 v[84:87], v[144:147], v[194:197], v[84:87]
	v_mfma_f32_16x16x32_bf16 v[76:79], v[152:155], v[194:197], v[76:79]
	v_mfma_f32_16x16x32_bf16 v[68:71], v[144:147], v[224:227], v[68:71]
	v_mfma_f32_16x16x32_bf16 v[64:67], v[152:155], v[224:227], v[64:67]
	v_mfma_f32_16x16x32_bf16 v[116:119], v[148:151], v[164:167], v[116:119]
	v_mfma_f32_16x16x32_bf16 v[108:111], v[156:159], v[164:167], v[108:111]
	v_mfma_f32_16x16x32_bf16 v[100:103], v[148:151], v[190:193], v[100:103]
	v_mfma_f32_16x16x32_bf16 v[92:95], v[156:159], v[190:193], v[92:95]
	v_mfma_f32_16x16x32_bf16 v[84:87], v[148:151], v[198:201], v[84:87]
	v_mfma_f32_16x16x32_bf16 v[76:79], v[156:159], v[198:201], v[76:79]
	v_mfma_f32_16x16x32_bf16 v[68:71], v[148:151], v[230:233], v[68:71]
	v_mfma_f32_16x16x32_bf16 v[64:67], v[156:159], v[230:233], v[64:67]
	s_barrier
; #define PG8_STAGE(bufoff, gbase, voff) do { _Pragma("unroll") for (int _i = 0; _i < 2; ++_i) \
;         __builtin_amdgcn_global_load_lds((const unsigned*)((const char*)(gbase) + (voff)[_i]), (PG8_LAS unsigned*)(lds + (bufoff) + ldsw + _i * 8192), 16, 0, 0); } while (0)
; #define PG8_LDA(dst, b, h) do { _Pragma("unroll") for (int m = 0; m < 4; ++m) _Pragma("unroll") for (int k = 0; k < 2; ++k) dst[m][k] = *(const PG8_LAS bf16x8*)(lds + PG8_SA(b, h) + aoff + m * 2048 + k * 1024); } while (0)
; #define PG8_LDB(dst, b, h) do { _Pragma("unroll") for (int n = 0; n < 2; ++n) _Pragma("unroll") for (int k = 0; k < 2; ++k) dst[n][k] = *(const PG8_LAS bf16x8*)(lds + PG8_SB(b, h) + boff + n * 2048 + k * 1024); } while (0)
; #define PG8_MMA(ai, bj, At, Bt) do { __builtin_amdgcn_s_setprio(1); _Pragma("unroll") for (int m = 0; m < 4; ++m) _Pragma("unroll") for (int n = 0; n < 2; ++n) _Pragma("unroll") for (int k = 0; k < 2; ++k) \
;         acc[ai][bj][m][n] = __builtin_amdgcn_mfma_f32_16x16x32_bf16(Bt[n][k], At[m][k], acc[ai][bj][m][n], 0, 0, 0); __builtin_amdgcn_s_setprio(0); } while (0)
; #define PG8_WAIT_V(n) asm volatile("s_waitcnt vmcnt(" #n ")" ::: "memory")
; #define PG8_WAIT_L(n) asm volatile("s_waitcnt lgkmcnt(" #n ")" ::: "memory")
; #define PG8_BAR __builtin_amdgcn_s_barrier()
; #define PG8_SCHED __builtin_amdgcn_sched_barrier(0)
; __device__ __forceinline__ float row_rs(const float* part, int row, int fq) {
;     const f32x4 v = *(const f32x4*)(part + (size_t)row * 16 + 4 * fq);
;     float s = (v[0] + v[1]) + (v[2] + v[3]); s += __shfl_xor(s, 16); s += __shfl_xor(s, 32);
;     return rsqrtf(s * (1.0f / 1024.0f) + 1e-6f);
; template <class Epi, class Sched, bool ALIGN_EPI = false, bool SP2 = false>
; __device__ __forceinline__ void gemm_phase(PG8_LAS unsigned char* lds, const Gemm g, const Sched& S, const Epi& E) {
;     ...
;             PG8_LDB(B0, 1, 0); PG8_LDB(B1, 1, 1); PG8_SCHED; PG8_LDA(At, 1, 0); PG8_STAGE(PG8_SA(0, 1), a2 + hstep, voffA);
;             PG8_WAIT_V(8); PG8_WAIT_L(0); PG8_BAR; PG8_MMA(0, 0, At, B0); PG8_MMA(0, 1, At, B1); PG8_BAR; PG8_SCHED;
;             PG8_LDA(At, 1, 1); PG8_STAGE(PG8_SB(1, 0), b3, voffB); PG8_STAGE(PG8_SB(1, 1), b3 + hstep, voffB); PG8_STAGE(PG8_SA(1, 0), a3, voffA);
;             PG8_WAIT_V(8); PG8_WAIT_L(0); PG8_BAR; PG8_MMA(1, 0, At, B0); PG8_MMA(1, 1, At, B1); PG8_BAR; PG8_SCHED;
	s_setprio 0
	s_add_i32 s60, s76, s46
	v_lshl_add_u64 v[202:203], v[202:203], 0, s[70:71]
	s_mov_b32 m0, s60
	ds_read_b128 v[160:163], v219 offset:49152
	ds_read_b128 v[164:167], v219 offset:50176
	ds_read_b128 v[186:189], v219 offset:51200
	ds_read_b128 v[190:193], v219 offset:52224
	ds_read_b128 v[194:197], v219 offset:53248
	ds_read_b128 v[198:201], v219 offset:54272
	ds_read_b128 v[224:227], v219 offset:55296
	ds_read_b128 v[230:233], v219 offset:56320
	global_load_lds_dwordx4 v[202:203], off
	s_add_i32 m0, s60, 0x2000
	s_add_u32 s54, s54, 0x40080
	v_lshl_add_u64 v[202:203], v[208:209], 0, s[70:71]
	s_addc_u32 s55, s55, 0
	s_add_i32 s60, s77, s46
	global_load_lds_dwordx4 v[202:203], off
	v_lshl_add_u64 v[202:203], s[54:55], 0, v[180:181]
	s_mov_b32 m0, s60
	s_nop 0
	global_load_lds_dwordx4 v[202:203], off
	v_lshl_add_u64 v[202:203], s[54:55], 0, v[168:169]
	s_add_i32 m0, s60, 0x2000
	s_nop 0
	global_load_lds_dwordx4 v[202:203], off
	v_lshl_add_u64 v[202:203], v[220:221], 0, s[70:71]
	s_mov_b32 m0, s59
	s_nop 0
	global_load_lds_dwordx4 v[202:203], off
	v_lshl_add_u64 v[202:203], v[234:235], 0, s[70:71]
	s_mov_b32 m0, s68
	s_nop 0
	global_load_lds_dwordx4 v[202:203], off
	s_waitcnt vmcnt(8)
	s_waitcnt lgkmcnt(0)
	s_setprio 1
	s_barrier
	v_mfma_f32_16x16x32_bf16 v[60:63], v[128:131], v[160:163], v[60:63]
	v_mfma_f32_16x16x32_bf16 v[56:59], v[136:139], v[160:163], v[56:59]
	v_mfma_f32_16x16x32_bf16 v[48:51], v[128:131], v[186:189], v[48:51]
	v_mfma_f32_16x16x32_bf16 v[40:43], v[136:139], v[186:189], v[40:43]
	v_mfma_f32_16x16x32_bf16 v[32:35], v[128:131], v[194:197], v[32:35]
	v_mfma_f32_16x16x32_bf16 v[24:27], v[136:139], v[194:197], v[24:27]
	v_mfma_f32_16x16x32_bf16 v[16:19], v[128:131], v[224:227], v[16:19]
	v_mfma_f32_16x16x32_bf16 v[8:11], v[136:139], v[224:227], v[8:11]
	v_mfma_f32_16x16x32_bf16 v[60:63], v[132:135], v[164:167], v[60:63]
	v_mfma_f32_16x16x32_bf16 v[56:59], v[140:143], v[164:167], v[56:59]
	v_mfma_f32_16x16x32_bf16 v[48:51], v[132:135], v[190:193], v[48:51]
	v_mfma_f32_16x16x32_bf16 v[40:43], v[140:143], v[190:193], v[40:43]
	v_mfma_f32_16x16x32_bf16 v[32:35], v[132:135], v[198:201], v[32:35]
	v_mfma_f32_16x16x32_bf16 v[24:27], v[140:143], v[198:201], v[24:27]
	v_mfma_f32_16x16x32_bf16 v[16:19], v[132:135], v[230:233], v[16:19]
	v_mfma_f32_16x16x32_bf16 v[8:11], v[140:143], v[230:233], v[8:11]
	s_setprio 0
	s_setprio 1
	v_mfma_f32_16x16x32_bf16 v[52:55], v[144:147], v[160:163], v[52:55]
	v_mfma_f32_16x16x32_bf16 v[44:47], v[152:155], v[160:163], v[44:47]
	v_mfma_f32_16x16x32_bf16 v[36:39], v[144:147], v[186:189], v[36:39]
	v_mfma_f32_16x16x32_bf16 v[28:31], v[152:155], v[186:189], v[28:31]
	v_mfma_f32_16x16x32_bf16 v[20:23], v[144:147], v[194:197], v[20:23]
	v_mfma_f32_16x16x32_bf16 v[12:15], v[152:155], v[194:197], v[12:15]
	v_mfma_f32_16x16x32_bf16 v[4:7], v[144:147], v[224:227], v[4:7]
	v_mfma_f32_16x16x32_bf16 v[0:3], v[152:155], v[224:227], v[0:3]
	v_mfma_f32_16x16x32_bf16 v[52:55], v[148:151], v[164:167], v[52:55]
	v_mfma_f32_16x16x32_bf16 v[44:47], v[156:159], v[164:167], v[44:47]
	v_mfma_f32_16x16x32_bf16 v[36:39], v[148:151], v[190:193], v[36:39]
	v_mfma_f32_16x16x32_bf16 v[28:31], v[156:159], v[190:193], v[28:31]
	v_mfma_f32_16x16x32_bf16 v[20:23], v[148:151], v[198:201], v[20:23]
	v_mfma_f32_16x16x32_bf16 v[12:15], v[156:159], v[198:201], v[12:15]
	v_mfma_f32_16x16x32_bf16 v[4:7], v[148:151], v[230:233], v[4:7]
	v_mfma_f32_16x16x32_bf16 v[0:3], v[156:159], v[230:233], v[0:3]
	s_barrier
	s_setprio 0
	s_add_i32 s73, s73, 2
	s_add_u32 s8, s8, 0x100
	s_addc_u32 s9, s9, 0
	s_add_u32 s62, s62, 0x100
	s_addc_u32 s63, s63, 0
	s_cmp_gt_u32 s73, 13
	s_cbranch_scc0 .LBB0_360
	s_and_b64 vcc, exec, s[18:19]
	s_cbranch_vccz .LBB0_363
	v_lshl_add_u32 v202, s3, 8, v228
	v_lshlrev_b32_e32 v202, 6, v202
	v_and_b32_e32 v165, 48, v228
	v_sub_u32_e32 v202, v202, v165
	v_mov_b32_e32 v203, 0
	v_lshl_add_u64 v[202:203], v[174:175], 0, v[202:203]
	global_load_dwordx4 v[186:189], v[202:203], off
	global_load_dwordx4 v[190:193], v[202:203], off offset:16
	global_load_dwordx4 v[194:197], v[202:203], off offset:32
	global_load_dwordx4 v[198:201], v[202:203], off offset:48
	v_lshlrev_b32_e32 v165, 2, v228
	v_add_u32_e32 v165, 0x20000, v165
	v_mov_b32_e32 v166, s74
	s_waitcnt vmcnt(0)
	v_add_f32_e32 v186, v186, v187
	v_add_f32_e32 v188, v188, v189
	v_add_f32_e32 v186, v186, v188
	v_add_f32_e32 v190, v190, v191
	v_add_f32_e32 v192, v192, v193
	v_add_f32_e32 v190, v190, v192
	v_add_f32_e32 v194, v194, v195
	v_add_f32_e32 v196, v196, v197
	v_add_f32_e32 v194, v194, v196
	v_add_f32_e32 v198, v198, v199
	v_add_f32_e32 v200, v200, v201
	v_add_f32_e32 v198, v198, v200
	v_add_f32_e32 v186, v186, v190
	v_add_f32_e32 v194, v194, v198
	v_add_f32_e32 v186, v186, v194
	v_fma_f32 v186, v186, s72, v166
	v_mul_f32_e32 v187, 0x4b800000, v186
	v_cmp_gt_f32_e32 vcc, s91, v186
	s_nop 1
	v_cndmask_b32_e32 v186, v186, v187, vcc
	v_rsq_f32_e32 v186, v186
	s_nop 0
	v_mul_f32_e32 v187, 0x45800000, v186
	v_cndmask_b32_e32 v186, v186, v187, vcc
	ds_write_b32 v165, v186
	s_waitcnt lgkmcnt(0)
	s_barrier

; __device__ __forceinline__ unsigned cvt_pk_bf16(float lo, float hi) { unsigned r; asm volatile("v_cvt_pk_bf16_f32 %0, %1, %2" : "=v"(r) : "v"(lo), "v"(hi)); return r; }
;     __device__ __forceinline__ void operator()(const f32x4 (&acc)[2][2][4][2], const Unit& u, int wr, int wc, int fr, int fq) const {
;         const int row0 = u.pm * BM + wr * 64 + fr, col0 = u.pn * BM + wc * 32 + 8 * fq;
;         f32x4 bv[2][2];
; #pragma unroll
;         for (int bj = 0; bj < 2; ++bj)
; #pragma unroll
;             for (int n = 0; n < 2; ++n) bv[bj][n] = bias ? *(const f32x4*)(bias + col0 + bj * HALF + 4 * n) : (f32x4){0.f, 0.f, 0.f, 0.f};
;         float rsv[2][4]; row_rs8(rsv, part, row0, fq);
; #pragma unroll
;         for (int ai = 0; ai < 2; ++ai)
; #pragma unroll
;             for (int m = 0; m < 4; ++m) { const int row = row0 + ai * HALF + m * 16; const float rs = rsv[ai][m];
; #pragma unroll
;                 for (int bj = 0; bj < 2; ++bj) { const f32x4 v0 = acc[ai][bj][m][0] * rs + bv[bj][0], v1 = acc[ai][bj][m][1] * rs + bv[bj][1];
;                     u32x4 w; w.x = cvt_pk_bf16(v0[0], v0[1]); w.y = cvt_pk_bf16(v0[2], v0[3]); w.z = cvt_pk_bf16(v1[0], v1[1]); w.w = cvt_pk_bf16(v1[2], v1[3]);
;                     __builtin_nontemporal_store(w, (u32x4*)(O + (size_t)row * ldc + col0 + bj * HALF)); } }
.LBB0_371:
	v_lshl_add_u32 v202, s3, 8, v216
	v_lshlrev_b32_e32 v165, 2, v216
	v_add_u32_e32 v165, 0x20000, v165
	ds_read_b32 v146, v165
	ds_read_b32 v148, v165 offset:64
	ds_read_b32 v150, v165 offset:128
	ds_read_b32 v152, v165 offset:192
	ds_read_b32 v154, v165 offset:512
	ds_read_b32 v156, v165 offset:576
	ds_read_b32 v158, v165 offset:640
	ds_read_b32 v164, v165 offset:704
	v_mov_b64_e32 v[160:161], s[14:15]
	v_lshlrev_b64 v[162:163], 1, v[196:197]
	s_andn2_b64 vcc, exec, s[6:7]
	s_waitcnt vmcnt(0)
	s_waitcnt lgkmcnt(0)
	v_mov_b32_e32 v200, v202
	v_mad_i64_i32 v[166:167], s[8:9], v200, s30, v[160:161]
	v_lshl_add_u64 v[166:167], v[166:167], 0, v[162:163]
	v_pk_fma_f32 v[124:125], v[124:125], v[146:147], v[132:133] op_sel_hi:[1,0,1]
	v_pk_fma_f32 v[126:127], v[126:127], v[146:147], v[134:135] op_sel_hi:[1,0,1]
	v_pk_fma_f32 v[120:121], v[120:121], v[146:147], v[128:129] op_sel_hi:[1,0,1]
	v_pk_fma_f32 v[122:123], v[122:123], v[146:147], v[130:131] op_sel_hi:[1,0,1]
	v_cvt_pk_bf16_f32 v124, v124, v125
	v_cvt_pk_bf16_f32 v125, v126, v127
	v_cvt_pk_bf16_f32 v126, v120, v121
	v_cvt_pk_bf16_f32 v127, v122, v123
	global_store_dwordx4 v[166:167], v[124:127], off nt
	v_pk_fma_f32 v[116:117], v[116:117], v[146:147], v[140:141] op_sel_hi:[1,0,1]
	v_pk_fma_f32 v[118:119], v[118:119], v[146:147], v[142:143] op_sel_hi:[1,0,1]
	v_pk_fma_f32 v[108:109], v[108:109], v[146:147], v[136:137] op_sel_hi:[1,0,1]
	v_pk_fma_f32 v[110:111], v[110:111], v[146:147], v[138:139] op_sel_hi:[1,0,1]
	v_cvt_pk_bf16_f32 v116, v116, v117
	v_cvt_pk_bf16_f32 v117, v118, v119
	v_cvt_pk_bf16_f32 v118, v108, v109
	v_cvt_pk_bf16_f32 v119, v110, v111
	global_store_dwordx4 v[166:167], v[116:119], off offset:256 nt
	v_add_u32_e32 v200, 0x10, v202
	v_mad_i64_i32 v[166:167], s[8:9], v200, s30, v[160:161]
	v_lshl_add_u64 v[166:167], v[166:167], 0, v[162:163]
	v_pk_fma_f32 v[112:113], v[112:113], v[148:149], v[132:133] op_sel_hi:[1,0,1]
	v_pk_fma_f32 v[114:115], v[114:115], v[148:149], v[134:135] op_sel_hi:[1,0,1]
	v_pk_fma_f32 v[104:105], v[104:105], v[148:149], v[128:129] op_sel_hi:[1,0,1]
	v_pk_fma_f32 v[106:107], v[106:107], v[148:149], v[130:131] op_sel_hi:[1,0,1]
	v_cvt_pk_bf16_f32 v112, v112, v113
	v_cvt_pk_bf16_f32 v113, v114, v115
	v_cvt_pk_bf16_f32 v114, v104, v105
	v_cvt_pk_bf16_f32 v115, v106, v107
	global_store_dwordx4 v[166:167], v[112:115], off nt
	v_pk_fma_f32 v[100:101], v[100:101], v[148:149], v[140:141] op_sel_hi:[1,0,1]
	v_pk_fma_f32 v[102:103], v[102:103], v[148:149], v[142:143] op_sel_hi:[1,0,1]
	v_pk_fma_f32 v[92:93], v[92:93], v[148:149], v[136:137] op_sel_hi:[1,0,1]
	v_pk_fma_f32 v[94:95], v[94:95], v[148:149], v[138:139] op_sel_hi:[1,0,1]
	v_cvt_pk_bf16_f32 v100, v100, v101
	v_cvt_pk_bf16_f32 v101, v102, v103
	v_cvt_pk_bf16_f32 v102, v92, v93
	v_cvt_pk_bf16_f32 v103, v94, v95
	global_store_dwordx4 v[166:167], v[100:103], off offset:256 nt
	v_add_u32_e32 v200, 0x20, v202
	v_mad_i64_i32 v[166:167], s[8:9], v200, s30, v[160:161]
	v_lshl_add_u64 v[166:167], v[166:167], 0, v[162:163]
	v_pk_fma_f32 v[96:97], v[96:97], v[150:151], v[132:133] op_sel_hi:[1,0,1]
	v_pk_fma_f32 v[98:99], v[98:99], v[150:151], v[134:135] op_sel_hi:[1,0,1]
	v_pk_fma_f32 v[88:89], v[88:89], v[150:151], v[128:129] op_sel_hi:[1,0,1]
	v_pk_fma_f32 v[90:91], v[90:91], v[150:151], v[130:131] op_sel_hi:[1,0,1]
	v_cvt_pk_bf16_f32 v96, v96, v97
	v_cvt_pk_bf16_f32 v97, v98, v99
	v_cvt_pk_bf16_f32 v98, v88, v89
	v_cvt_pk_bf16_f32 v99, v90, v91
	global_store_dwordx4 v[166:167], v[96:99], off nt
	v_pk_fma_f32 v[84:85], v[84:85], v[150:151], v[140:141] op_sel_hi:[1,0,1]
	v_pk_fma_f32 v[86:87], v[86:87], v[150:151], v[142:143] op_sel_hi:[1,0,1]
	v_pk_fma_f32 v[76:77], v[76:77], v[150:151], v[136:137] op_sel_hi:[1,0,1]
	v_pk_fma_f32 v[78:79], v[78:79], v[150:151], v[138:139] op_sel_hi:[1,0,1]
	v_cvt_pk_bf16_f32 v84, v84, v85
	v_cvt_pk_bf16_f32 v85, v86, v87
	v_cvt_pk_bf16_f32 v86, v76, v77
	v_cvt_pk_bf16_f32 v87, v78, v79
	global_store_dwordx4 v[166:167], v[84:87], off offset:256 nt
	v_add_u32_e32 v200, 0x30, v202
	v_mad_i64_i32 v[166:167], s[8:9], v200, s30, v[160:161]
	v_lshl_add_u64 v[166:167], v[166:167], 0, v[162:163]
	v_pk_fma_f32 v[80:81], v[80:81], v[152:153], v[132:133] op_sel_hi:[1,0,1]
	v_pk_fma_f32 v[82:83], v[82:83], v[152:153], v[134:135] op_sel_hi:[1,0,1]
	v_pk_fma_f32 v[72:73], v[72:73], v[152:153], v[128:129] op_sel_hi:[1,0,1]
	v_pk_fma_f32 v[74:75], v[74:75], v[152:153], v[130:131] op_sel_hi:[1,0,1]
	v_cvt_pk_bf16_f32 v80, v80, v81
	v_cvt_pk_bf16_f32 v81, v82, v83
	v_cvt_pk_bf16_f32 v82, v72, v73
	v_cvt_pk_bf16_f32 v83, v74, v75
	global_store_dwordx4 v[166:167], v[80:83], off nt
	v_pk_fma_f32 v[68:69], v[68:69], v[152:153], v[140:141] op_sel_hi:[1,0,1]
	v_pk_fma_f32 v[70:71], v[70:71], v[152:153], v[142:143] op_sel_hi:[1,0,1]
	v_pk_fma_f32 v[64:65], v[64:65], v[152:153], v[136:137] op_sel_hi:[1,0,1]
; __device__ __forceinline__ unsigned cvt_pk_bf16(float lo, float hi) { unsigned r; asm volatile("v_cvt_pk_bf16_f32 %0, %1, %2" : "=v"(r) : "v"(lo), "v"(hi)); return r; }
;     __device__ __forceinline__ void operator()(const f32x4 (&acc)[2][2][4][2], const Unit& u, int wr, int wc, int fr, int fq) const {
;     ...
;         for (int ai = 0; ai < 2; ++ai)
; #pragma unroll
;             for (int m = 0; m < 4; ++m) { const int row = row0 + ai * HALF + m * 16; const float rs = rsv[ai][m];
; #pragma unroll
;                 for (int bj = 0; bj < 2; ++bj) { const f32x4 v0 = acc[ai][bj][m][0] * rs + bv[bj][0], v1 = acc[ai][bj][m][1] * rs + bv[bj][1];
;                     u32x4 w; w.x = cvt_pk_bf16(v0[0], v0[1]); w.y = cvt_pk_bf16(v0[2], v0[3]); w.z = cvt_pk_bf16(v1[0], v1[1]); w.w = cvt_pk_bf16(v1[2], v1[3]);
;                     __builtin_nontemporal_store(w, (u32x4*)(O + (size_t)row * ldc + col0 + bj * HALF)); } }
	v_pk_fma_f32 v[66:67], v[66:67], v[152:153], v[138:139] op_sel_hi:[1,0,1]
	v_cvt_pk_bf16_f32 v68, v68, v69
	v_cvt_pk_bf16_f32 v69, v70, v71
	v_cvt_pk_bf16_f32 v70, v64, v65
	v_cvt_pk_bf16_f32 v71, v66, v67
	global_store_dwordx4 v[166:167], v[68:71], off offset:256 nt
	v_add_u32_e32 v200, 0x80, v202
	v_mad_i64_i32 v[166:167], s[8:9], v200, s30, v[160:161]
	v_lshl_add_u64 v[166:167], v[166:167], 0, v[162:163]
	v_pk_fma_f32 v[60:61], v[60:61], v[154:155], v[132:133] op_sel_hi:[1,0,1]
	v_pk_fma_f32 v[62:63], v[62:63], v[154:155], v[134:135] op_sel_hi:[1,0,1]
	v_pk_fma_f32 v[56:57], v[56:57], v[154:155], v[128:129] op_sel_hi:[1,0,1]
	v_pk_fma_f32 v[58:59], v[58:59], v[154:155], v[130:131] op_sel_hi:[1,0,1]
	v_cvt_pk_bf16_f32 v60, v60, v61
	v_cvt_pk_bf16_f32 v61, v62, v63
	v_cvt_pk_bf16_f32 v62, v56, v57
	v_cvt_pk_bf16_f32 v63, v58, v59
	global_store_dwordx4 v[166:167], v[60:63], off nt
	v_pk_fma_f32 v[52:53], v[52:53], v[154:155], v[140:141] op_sel_hi:[1,0,1]
	v_pk_fma_f32 v[54:55], v[54:55], v[154:155], v[142:143] op_sel_hi:[1,0,1]
	v_pk_fma_f32 v[44:45], v[44:45], v[154:155], v[136:137] op_sel_hi:[1,0,1]
	v_pk_fma_f32 v[46:47], v[46:47], v[154:155], v[138:139] op_sel_hi:[1,0,1]
	v_cvt_pk_bf16_f32 v52, v52, v53
	v_cvt_pk_bf16_f32 v53, v54, v55
	v_cvt_pk_bf16_f32 v54, v44, v45
	v_cvt_pk_bf16_f32 v55, v46, v47
	global_store_dwordx4 v[166:167], v[52:55], off offset:256 nt
	v_add_u32_e32 v200, 0x90, v202
	v_mad_i64_i32 v[166:167], s[8:9], v200, s30, v[160:161]
	v_lshl_add_u64 v[166:167], v[166:167], 0, v[162:163]
	v_pk_fma_f32 v[48:49], v[48:49], v[156:157], v[132:133] op_sel_hi:[1,0,1]
	v_pk_fma_f32 v[50:51], v[50:51], v[156:157], v[134:135] op_sel_hi:[1,0,1]
	v_pk_fma_f32 v[40:41], v[40:41], v[156:157], v[128:129] op_sel_hi:[1,0,1]
	v_pk_fma_f32 v[42:43], v[42:43], v[156:157], v[130:131] op_sel_hi:[1,0,1]
	v_cvt_pk_bf16_f32 v48, v48, v49
	v_cvt_pk_bf16_f32 v49, v50, v51
	v_cvt_pk_bf16_f32 v50, v40, v41
	v_cvt_pk_bf16_f32 v51, v42, v43
	global_store_dwordx4 v[166:167], v[48:51], off nt
	v_pk_fma_f32 v[36:37], v[36:37], v[156:157], v[140:141] op_sel_hi:[1,0,1]
	v_pk_fma_f32 v[38:39], v[38:39], v[156:157], v[142:143] op_sel_hi:[1,0,1]
	v_pk_fma_f32 v[28:29], v[28:29], v[156:157], v[136:137] op_sel_hi:[1,0,1]
	v_pk_fma_f32 v[30:31], v[30:31], v[156:157], v[138:139] op_sel_hi:[1,0,1]
	v_cvt_pk_bf16_f32 v36, v36, v37
	v_cvt_pk_bf16_f32 v37, v38, v39
	v_cvt_pk_bf16_f32 v38, v28, v29
	v_cvt_pk_bf16_f32 v39, v30, v31
	global_store_dwordx4 v[166:167], v[36:39], off offset:256 nt
	v_add_u32_e32 v200, 0xa0, v202
	v_mad_i64_i32 v[166:167], s[8:9], v200, s30, v[160:161]
	v_lshl_add_u64 v[166:167], v[166:167], 0, v[162:163]
	v_pk_fma_f32 v[32:33], v[32:33], v[158:159], v[132:133] op_sel_hi:[1,0,1]
	v_pk_fma_f32 v[34:35], v[34:35], v[158:159], v[134:135] op_sel_hi:[1,0,1]
	v_pk_fma_f32 v[24:25], v[24:25], v[158:159], v[128:129] op_sel_hi:[1,0,1]
	v_pk_fma_f32 v[26:27], v[26:27], v[158:159], v[130:131] op_sel_hi:[1,0,1]
	v_cvt_pk_bf16_f32 v32, v32, v33
	v_cvt_pk_bf16_f32 v33, v34, v35
	v_cvt_pk_bf16_f32 v34, v24, v25
	v_cvt_pk_bf16_f32 v35, v26, v27
	global_store_dwordx4 v[166:167], v[32:35], off nt
	v_pk_fma_f32 v[20:21], v[20:21], v[158:159], v[140:141] op_sel_hi:[1,0,1]
	v_pk_fma_f32 v[22:23], v[22:23], v[158:159], v[142:143] op_sel_hi:[1,0,1]
	v_pk_fma_f32 v[12:13], v[12:13], v[158:159], v[136:137] op_sel_hi:[1,0,1]
	v_pk_fma_f32 v[14:15], v[14:15], v[158:159], v[138:139] op_sel_hi:[1,0,1]
	v_cvt_pk_bf16_f32 v20, v20, v21
	v_cvt_pk_bf16_f32 v21, v22, v23
	v_cvt_pk_bf16_f32 v22, v12, v13
	v_cvt_pk_bf16_f32 v23, v14, v15
	global_store_dwordx4 v[166:167], v[20:23], off offset:256 nt
	v_add_u32_e32 v200, 0xb0, v202
	v_mad_i64_i32 v[166:167], s[8:9], v200, s30, v[160:161]
	v_lshl_add_u64 v[166:167], v[166:167], 0, v[162:163]
	v_pk_fma_f32 v[16:17], v[16:17], v[164:165], v[132:133] op_sel_hi:[1,0,1]
	v_pk_fma_f32 v[18:19], v[18:19], v[164:165], v[134:135] op_sel_hi:[1,0,1]
	v_pk_fma_f32 v[8:9], v[8:9], v[164:165], v[128:129] op_sel_hi:[1,0,1]
	v_pk_fma_f32 v[10:11], v[10:11], v[164:165], v[130:131] op_sel_hi:[1,0,1]
	v_cvt_pk_bf16_f32 v16, v16, v17
	v_cvt_pk_bf16_f32 v17, v18, v19
	v_cvt_pk_bf16_f32 v18, v8, v9
	v_cvt_pk_bf16_f32 v19, v10, v11
	global_store_dwordx4 v[166:167], v[16:19], off nt
	v_pk_fma_f32 v[4:5], v[4:5], v[164:165], v[140:141] op_sel_hi:[1,0,1]
	v_pk_fma_f32 v[6:7], v[6:7], v[164:165], v[142:143] op_sel_hi:[1,0,1]
	v_pk_fma_f32 v[0:1], v[0:1], v[164:165], v[136:137] op_sel_hi:[1,0,1]
	v_pk_fma_f32 v[2:3], v[2:3], v[164:165], v[138:139] op_sel_hi:[1,0,1]
	v_cvt_pk_bf16_f32 v4, v4, v5
	v_cvt_pk_bf16_f32 v5, v6, v7
	v_cvt_pk_bf16_f32 v6, v0, v1
	v_cvt_pk_bf16_f32 v7, v2, v3
	s_mov_b64 s[8:9], -1
	global_store_dwordx4 v[166:167], v[4:7], off offset:256 nt
	s_cbranch_vccnz .LBB0_356
	s_andn2_b64 vcc, exec, s[10:11]
	s_cbranch_vccnz .LBB0_355
	s_barrier
	s_branch .LBB0_355
